# ffn-in GEMM: peeled first K-iteration of non-first tiles waits with vmcnt(16), not for the previous tile's 8 H stores
# speedup vs baseline: 1.0069x; 1.0014x over previous
.LBB0_1112:
	s_cmp_lt_i32 s94, 11
	s_cselect_b64 s[2:3], -1, 0
	s_and_b64 s[4:5], s[2:3], s[0:1]
	s_andn2_b64 vcc, exec, s[4:5]
	s_cbranch_vccnz .LBB0_1129
	s_mov_b32 s96, 0
	v_mov_b32_e32 v9, v196
	s_cmpk_gt_i32 s33, 0x57f
	s_nop 0
	v_readfirstlane_b32 s1, v9
	s_cbranch_scc1 .LBB0_1129
	v_lshlrev_b32_e32 v0, 4, v9
	v_add_u32_e32 v1, 0x2000, v0
	v_ashrrev_i32_e32 v2, 31, v1
	v_lshrrev_b32_e32 v2, 22, v2
	v_add_u32_e32 v2, v1, v2
	v_ashrrev_i32_e32 v8, 10, v2
	v_mul_i32_i24_e32 v2, 0x400, v8
	v_sub_u32_e32 v1, v1, v2
	v_lshrrev_b32_e32 v2, 4, v1
	v_bitop3_b32 v1, v2, v1, 32 bitop3:0x6c
	v_ashrrev_i32_e32 v2, 31, v1
	v_lshrrev_b32_e32 v2, 26, v2
	v_add_u32_e32 v2, v1, v2
	v_lshlrev_b32_e32 v3, 3, v8
	v_ashrrev_i32_e32 v10, 6, v2
	v_and_b32_e32 v3, -16, v3
	v_add_u32_e32 v3, v10, v3
	v_and_b32_e32 v4, 3, v10
	s_mov_b32 s0, 0x1fffe0
	v_lshrrev_b32_e32 v5, 2, v3
	v_lshlrev_b32_e32 v6, 1, v3
	v_and_b32_e32 v2, 0xc0, v2
	v_and_or_b32 v4, v3, s0, v4
	v_and_b32_e32 v5, 4, v5
	v_and_b32_e32 v6, 24, v6
	v_sub_u32_e32 v1, v1, v2
	v_mov_b32_e32 v2, 1
	v_or3_b32 v4, v4, v5, v6
	v_lshlrev_b32_e32 v5, 5, v8
	v_ashrrev_i16_sdwa v1, v2, sext(v1) dst_sel:DWORD dst_unused:UNUSED_PAD src0_sel:DWORD src1_sel:BYTE_0
	v_and_b32_e32 v5, 32, v5
	v_bfe_i32 v11, v1, 0, 16
	v_add_lshl_u32 v1, v5, v11, 1
	v_lshl_add_u32 v128, v4, 11, v1
	v_lshl_add_u32 v130, v3, 11, v1
	v_bfe_i32 v1, v9, 27, 1
	v_lshrrev_b32_e32 v1, 22, v1
	v_add_u32_e32 v1, v0, v1
	v_and_b32_e32 v1, 0xfffffc00, v1
	v_sub_u32_e32 v0, v0, v1
	v_lshrrev_b32_e32 v1, 4, v0
	v_ashrrev_i32_e32 v3, 31, v9
	v_bitop3_b32 v0, v1, v0, 32 bitop3:0x6c
	v_lshrrev_b32_e32 v3, 26, v3
	v_ashrrev_i32_e32 v1, 31, v0
	v_add_u32_e32 v3, v9, v3
	v_lshrrev_b32_e32 v1, 26, v1
	v_ashrrev_i32_e32 v13, 6, v3
	v_add_u32_e32 v1, v0, v1
	v_lshlrev_b32_e32 v3, 3, v13
	v_ashrrev_i32_e32 v12, 6, v1
	v_and_b32_e32 v3, -16, v3
	v_add_u32_e32 v3, v12, v3
	v_and_b32_e32 v4, 3, v12
	s_ashr_i32 s3, s33, 31
	v_and_or_b32 v4, v3, s0, v4
	s_lshr_b32 s0, s3, 29
	s_add_i32 s0, s33, s0
	s_ashr_i32 s12, s1, 6
	s_ashr_i32 s10, s0, 3
	s_and_b32 s0, s0, -8
	s_ashr_i32 s13, s1, 8
	s_lshl_b32 s2, s12, 10
	s_sub_i32 s0, s33, s0
	s_cmp_lt_i32 s0, 0
	s_movk_i32 s14, 0xb1
	s_cselect_b32 s11, s14, 0xb0
	s_mul_i32 s0, s0, s11
	s_add_i32 s0, s0, s10
	s_mul_hi_i32 s10, s0, 0x2e8ba2e9
	s_lshr_b32 s11, s10, 31
	s_ashr_i32 s10, s10, 5
	s_add_i32 s10, s10, s11
	s_lshl_b32 s11, s10, 3
	s_mulk_i32 s10, 0xb0
	s_sub_i32 s10, s0, s10
	s_sext_i32_i16 s0, s10
	s_bfe_u32 s0, s0, 0x3001c
	s_add_i32 s15, s10, s0
	s_sext_i32_i16 s0, s15
	s_and_b32 s15, s15, 0xfff8
	s_sub_i32 s10, s10, s15
	s_sext_i32_i16 s10, s10
	v_lshrrev_b32_e32 v5, 2, v3
	v_lshlrev_b32_e32 v6, 1, v3
	v_and_b32_e32 v1, 0xc0, v1
	s_lshr_b32 s0, s0, 3
	s_add_i32 s28, s11, s10
	v_and_b32_e32 v5, 4, v5
	v_and_b32_e32 v6, 24, v6
	v_sub_u32_e32 v0, v0, v1
	s_ashr_i32 s29, s28, 31
	s_bfe_i64 s[16:17], s[0:1], 0x100000
	v_or3_b32 v4, v4, v5, v6
	v_lshlrev_b32_e32 v5, 5, v13
	v_ashrrev_i16_sdwa v0, v2, sext(v0) dst_sel:DWORD dst_unused:UNUSED_PAD src0_sel:DWORD src1_sel:BYTE_0
	s_lshl_b64 s[10:11], s[28:29], 19
	s_lshl_b64 s[16:17], s[16:17], 19
	v_and_b32_e32 v5, 32, v5
	v_bfe_i32 v14, v0, 0, 16
	s_add_u32 s40, s42, s16
	v_add_lshl_u32 v0, v5, v14, 1
	s_addc_u32 s41, s43, s17
	s_add_i32 s15, s2, 0
	v_lshl_add_u32 v132, v4, 11, v0
	s_add_i32 m0, s15, 0x10000
	v_lshl_add_u32 v134, v3, 11, v0
	global_load_lds_dwordx4 v132, s[40:41]
	s_add_i32 m0, s15, 0x12000
	s_add_u32 s16, s40, 0x40000
	global_load_lds_dwordx4 v128, s[40:41]
	s_addc_u32 s17, s41, 0
	s_add_i32 m0, s15, 0x14000
	v_mov_b32_e32 v137, 0
	global_load_lds_dwordx4 v132, s[16:17]
	s_add_i32 m0, s15, 0x16000
	s_add_u32 s36, s34, s10
	s_addc_u32 s37, s35, s11
	s_add_i32 s46, s15, 0x2000
	global_load_lds_dwordx4 v128, s[16:17]
	s_mov_b32 m0, s15
	s_add_u32 s10, s36, 0x40000
	global_load_lds_dwordx4 v134, s[36:37]
	s_mov_b32 m0, s46
	s_addc_u32 s11, s37, 0
	s_add_i32 s47, s15, 0x4000
	global_load_lds_dwordx4 v130, s[36:37]
	s_mov_b32 m0, s47
	s_add_i32 s48, s15, 0x6000
	global_load_lds_dwordx4 v134, s[10:11]
	s_mov_b32 m0, s48
	v_mov_b32_e32 v133, v137
	global_load_lds_dwordx4 v130, s[10:11]
	v_mov_b32_e32 v129, v137
	v_mov_b32_e32 v135, v137
	v_mov_b32_e32 v131, v137
	s_cmp_eq_u32 s13, 1
	s_mov_b32 s49, 0
	v_lshl_add_u64 v[6:7], s[40:41], 0, v[132:133]
	v_lshl_add_u64 v[4:5], s[40:41], 0, v[128:129]
	v_lshl_add_u64 v[0:1], s[36:37], 0, v[134:135]
	s_cselect_b64 s[10:11], -1, 0
	s_cmp_lg_u32 s13, 1
	v_lshl_add_u64 v[2:3], s[36:37], 0, v[130:131]
	s_cbranch_scc1 .LBB0_1116
	s_barrier

.LBB0_1118:
	s_mov_b32 s96, 1
	s_andn2_b64 vcc, exec, s[0:1]
	s_mov_b32 s29, s20
	s_mov_b32 s28, s22
	s_mov_b64 s[40:41], s[26:27]
	s_mov_b64 s[36:37], s[24:25]
	s_cbranch_vccz .LBB0_1128

.LBB0_1121:
	s_ashr_i32 s23, s22, 31
	s_lshl_b64 s[12:13], s[22:23], 19
	s_add_u32 s24, s34, s12
	s_addc_u32 s25, s35, s13
	s_and_b64 s[12:13], s[0:1], exec
	s_cselect_b32 s12, s25, s37
	s_cselect_b32 s13, s24, s36
	s_ashr_i32 s21, s20, 31
	s_lshl_b64 s[26:27], s[20:21], 19
	s_add_u32 s26, s42, s26
	s_addc_u32 s27, s43, s27
	s_and_b64 s[44:45], s[0:1], exec
	s_cselect_b32 s21, s27, s41
	s_cselect_b32 s23, s26, s40
	s_add_u32 s36, s36, 0x40080
	s_addc_u32 s37, s37, 0
	s_add_u32 s61, s40, 0x100
	s_addc_u32 s62, s41, 0
	s_mov_b32 s63, -2
	ds_read_b128 v[156:159], v151
	ds_read_b128 v[160:163], v151 offset:1024
	ds_read_b128 v[164:167], v151 offset:2048
	ds_read_b128 v[168:171], v151 offset:3072
	ds_read_b128 v[172:175], v152
	ds_read_b128 v[176:179], v152 offset:1024
	ds_read_b128 v[180:183], v152 offset:2048
	ds_read_b128 v[184:187], v152 offset:3072
	s_add_u32 s40, s36, 0xfffc0080
	s_addc_u32 s41, s37, -1
	s_cmp_eq_u32 s63, 12
	s_cselect_b32 s45, s12, s41
	s_cselect_b32 s44, s13, s40
	s_cselect_b32 s41, s21, s62
	s_cselect_b32 s40, s23, s61
	v_lshl_add_u64 v[148:149], s[36:37], 0, v[140:141]
	s_add_i32 m0, s15, 0xc000
	ds_read_b128 v[188:191], v153
	ds_read_b128 v[192:195], v153 offset:1024
	ds_read_b128 v[198:201], v153 offset:2048
	ds_read_b128 v[202:205], v153 offset:3072
	ds_read_b128 v[206:209], v153 offset:4096
	ds_read_b128 v[210:213], v153 offset:5120
	ds_read_b128 v[214:217], v153 offset:6144
	ds_read_b128 v[218:221], v153 offset:7168
	global_load_lds_dwordx4 v[148:149], off
	v_lshl_add_u64 v[148:149], s[36:37], 0, v[142:143]
	s_add_i32 m0, s15, 0xe000
	s_nop 0
	global_load_lds_dwordx4 v[148:149], off
	s_cmp_eq_u32 s96, 0
	s_cbranch_scc1 .Lp10_ws0
	s_waitcnt vmcnt(16)
	s_branch .Lp10_wd0

.Lp10_wd0:
	s_waitcnt lgkmcnt(0)
	s_barrier
	s_setprio 1
	s_waitcnt lgkmcnt(0)
	v_mfma_f32_16x16x32_bf16 v[124:127], v[156:159], v[188:191], 0
	v_mfma_f32_16x16x32_bf16 v[120:123], v[164:167], v[188:191], 0
	v_mfma_f32_16x16x32_bf16 v[108:111], v[156:159], v[198:201], 0
	v_mfma_f32_16x16x32_bf16 v[104:107], v[164:167], v[198:201], 0
	v_mfma_f32_16x16x32_bf16 v[92:95], v[156:159], v[206:209], 0
	v_mfma_f32_16x16x32_bf16 v[88:91], v[164:167], v[206:209], 0
	v_mfma_f32_16x16x32_bf16 v[76:79], v[156:159], v[214:217], 0
	v_mfma_f32_16x16x32_bf16 v[72:75], v[164:167], v[214:217], 0
	v_mfma_f32_16x16x32_bf16 v[124:127], v[160:163], v[192:195], v[124:127]
	v_mfma_f32_16x16x32_bf16 v[120:123], v[168:171], v[192:195], v[120:123]
	v_mfma_f32_16x16x32_bf16 v[108:111], v[160:163], v[202:205], v[108:111]
	v_mfma_f32_16x16x32_bf16 v[104:107], v[168:171], v[202:205], v[104:107]
	v_mfma_f32_16x16x32_bf16 v[92:95], v[160:163], v[210:213], v[92:95]
	v_mfma_f32_16x16x32_bf16 v[88:91], v[168:171], v[210:213], v[88:91]
	v_mfma_f32_16x16x32_bf16 v[76:79], v[160:163], v[218:221], v[76:79]
	v_mfma_f32_16x16x32_bf16 v[72:75], v[168:171], v[218:221], v[72:75]
	s_setprio 0
	s_setprio 1
	v_mfma_f32_16x16x32_bf16 v[116:119], v[172:175], v[188:191], 0
	v_mfma_f32_16x16x32_bf16 v[112:115], v[180:183], v[188:191], 0
	v_mfma_f32_16x16x32_bf16 v[100:103], v[172:175], v[198:201], 0
	v_mfma_f32_16x16x32_bf16 v[96:99], v[180:183], v[198:201], 0
	v_mfma_f32_16x16x32_bf16 v[84:87], v[172:175], v[206:209], 0
	v_mfma_f32_16x16x32_bf16 v[80:83], v[180:183], v[206:209], 0
	v_mfma_f32_16x16x32_bf16 v[68:71], v[172:175], v[214:217], 0
	v_mfma_f32_16x16x32_bf16 v[64:67], v[180:183], v[214:217], 0
	v_mfma_f32_16x16x32_bf16 v[116:119], v[176:179], v[192:195], v[116:119]
	v_mfma_f32_16x16x32_bf16 v[112:115], v[184:187], v[192:195], v[112:115]
	v_mfma_f32_16x16x32_bf16 v[100:103], v[176:179], v[202:205], v[100:103]
	v_mfma_f32_16x16x32_bf16 v[96:99], v[184:187], v[202:205], v[96:99]
	v_mfma_f32_16x16x32_bf16 v[84:87], v[176:179], v[210:213], v[84:87]
	v_mfma_f32_16x16x32_bf16 v[80:83], v[184:187], v[210:213], v[80:83]
	v_mfma_f32_16x16x32_bf16 v[68:71], v[176:179], v[218:221], v[68:71]
	v_mfma_f32_16x16x32_bf16 v[64:67], v[184:187], v[218:221], v[64:67]
	s_setprio 0
	s_barrier
	s_add_i32 s64, s57, s2
	v_lshl_add_u64 v[148:149], s[40:41], 0, v[132:133]
	s_mov_b32 m0, s64
	ds_read_b128 v[188:191], v153 offset:16384
	ds_read_b128 v[192:195], v153 offset:17408
	ds_read_b128 v[198:201], v153 offset:18432
	ds_read_b128 v[202:205], v153 offset:19456
	ds_read_b128 v[206:209], v153 offset:20480
	ds_read_b128 v[210:213], v153 offset:21504
	ds_read_b128 v[214:217], v153 offset:22528
	ds_read_b128 v[218:221], v153 offset:23552
	global_load_lds_dwordx4 v[148:149], off
	s_add_i32 m0, s64, 0x2000
	s_add_u32 s64, s40, 0x40000
	v_lshl_add_u64 v[222:223], s[40:41], 0, v[128:129]
	s_addc_u32 s65, s41, 0
	s_add_i32 s66, s58, s2
	global_load_lds_dwordx4 v[222:223], off
	v_lshl_add_u64 v[224:225], s[64:65], 0, v[132:133]
	s_mov_b32 m0, s66
	v_lshl_add_u64 v[226:227], s[44:45], 0, v[130:131]
	global_load_lds_dwordx4 v[224:225], off
	v_lshl_add_u64 v[224:225], s[64:65], 0, v[128:129]
	s_add_i32 m0, s66, 0x2000
	s_nop 0
	global_load_lds_dwordx4 v[224:225], off
	v_lshl_add_u64 v[224:225], s[44:45], 0, v[134:135]
	s_mov_b32 m0, s15
	s_nop 0
	global_load_lds_dwordx4 v[224:225], off
	s_mov_b32 m0, s46
	s_nop 0
	global_load_lds_dwordx4 v[226:227], off
	s_cmp_eq_u32 s96, 0
	s_cbranch_scc1 .Lp10_ws1
	s_waitcnt vmcnt(16)
	s_branch .Lp10_wd1

.Lp10_wd1:
	s_waitcnt lgkmcnt(0)
	s_barrier
	s_setprio 1
	s_waitcnt lgkmcnt(0)
	v_mfma_f32_16x16x32_bf16 v[60:63], v[156:159], v[188:191], 0
	v_mfma_f32_16x16x32_bf16 v[56:59], v[164:167], v[188:191], 0
	v_mfma_f32_16x16x32_bf16 v[44:47], v[156:159], v[198:201], 0
	v_mfma_f32_16x16x32_bf16 v[40:43], v[164:167], v[198:201], 0
	v_mfma_f32_16x16x32_bf16 v[28:31], v[156:159], v[206:209], 0
	v_mfma_f32_16x16x32_bf16 v[24:27], v[164:167], v[206:209], 0
	v_mfma_f32_16x16x32_bf16 v[12:15], v[156:159], v[214:217], 0
	v_mfma_f32_16x16x32_bf16 v[8:11], v[164:167], v[214:217], 0
	v_mfma_f32_16x16x32_bf16 v[60:63], v[160:163], v[192:195], v[60:63]
	v_mfma_f32_16x16x32_bf16 v[56:59], v[168:171], v[192:195], v[56:59]
	v_mfma_f32_16x16x32_bf16 v[44:47], v[160:163], v[202:205], v[44:47]
	v_mfma_f32_16x16x32_bf16 v[40:43], v[168:171], v[202:205], v[40:43]
	v_mfma_f32_16x16x32_bf16 v[28:31], v[160:163], v[210:213], v[28:31]
	v_mfma_f32_16x16x32_bf16 v[24:27], v[168:171], v[210:213], v[24:27]
	v_mfma_f32_16x16x32_bf16 v[12:15], v[160:163], v[218:221], v[12:15]
	v_mfma_f32_16x16x32_bf16 v[8:11], v[168:171], v[218:221], v[8:11]
	s_setprio 0
	s_setprio 1
	v_mfma_f32_16x16x32_bf16 v[52:55], v[172:175], v[188:191], 0
	v_mfma_f32_16x16x32_bf16 v[48:51], v[180:183], v[188:191], 0
	v_mfma_f32_16x16x32_bf16 v[36:39], v[172:175], v[198:201], 0
	v_mfma_f32_16x16x32_bf16 v[32:35], v[180:183], v[198:201], 0
	v_mfma_f32_16x16x32_bf16 v[20:23], v[172:175], v[206:209], 0
	v_mfma_f32_16x16x32_bf16 v[16:19], v[180:183], v[206:209], 0
	v_mfma_f32_16x16x32_bf16 v[4:7], v[172:175], v[214:217], 0
	v_mfma_f32_16x16x32_bf16 v[0:3], v[180:183], v[214:217], 0
	v_mfma_f32_16x16x32_bf16 v[52:55], v[176:179], v[192:195], v[52:55]
	v_mfma_f32_16x16x32_bf16 v[48:51], v[184:187], v[192:195], v[48:51]
	v_mfma_f32_16x16x32_bf16 v[36:39], v[176:179], v[202:205], v[36:39]
	v_mfma_f32_16x16x32_bf16 v[32:35], v[184:187], v[202:205], v[32:35]
	v_mfma_f32_16x16x32_bf16 v[20:23], v[176:179], v[210:213], v[20:23]
	v_mfma_f32_16x16x32_bf16 v[16:19], v[184:187], v[210:213], v[16:19]
	v_mfma_f32_16x16x32_bf16 v[4:7], v[176:179], v[218:221], v[4:7]
	v_mfma_f32_16x16x32_bf16 v[0:3], v[184:187], v[218:221], v[0:3]
	s_setprio 0
	s_barrier
	s_add_i32 s64, 0, 0x18000
	v_add_u32_e32 v136, s64, v150
	s_add_i32 s65, 0, 0x1c000
	ds_read_b128 v[156:159], v136
	ds_read_b128 v[160:163], v136 offset:1024
	ds_read_b128 v[164:167], v136 offset:2048
	ds_read_b128 v[168:171], v136 offset:3072
	v_add_u32_e32 v136, s65, v150
	ds_read_b128 v[172:175], v136
	ds_read_b128 v[176:179], v136 offset:1024
	ds_read_b128 v[180:183], v136 offset:2048
	ds_read_b128 v[184:187], v136 offset:3072
	s_add_u32 s44, s44, 0x40000
	s_addc_u32 s45, s45, 0
	s_mov_b32 m0, s47
	v_lshl_add_u64 v[228:229], s[44:45], 0, v[134:135]
	ds_read_b128 v[188:191], v153 offset:32768
	ds_read_b128 v[192:195], v153 offset:33792
	ds_read_b128 v[198:201], v153 offset:34816
	ds_read_b128 v[202:205], v153 offset:35840
	ds_read_b128 v[206:209], v153 offset:36864
	ds_read_b128 v[210:213], v153 offset:37888
	ds_read_b128 v[214:217], v153 offset:38912
	ds_read_b128 v[218:221], v153 offset:39936
	global_load_lds_dwordx4 v[228:229], off
	v_lshl_add_u64 v[228:229], s[44:45], 0, v[130:131]
	s_mov_b32 m0, s48
	s_nop 0
	global_load_lds_dwordx4 v[228:229], off
	s_waitcnt vmcnt(8)
	s_waitcnt lgkmcnt(0)
	s_barrier
	s_setprio 1
	s_waitcnt lgkmcnt(0)
	v_mfma_f32_16x16x32_bf16 v[124:127], v[156:159], v[188:191], v[124:127]
	v_mfma_f32_16x16x32_bf16 v[120:123], v[164:167], v[188:191], v[120:123]
	v_mfma_f32_16x16x32_bf16 v[108:111], v[156:159], v[198:201], v[108:111]
	v_mfma_f32_16x16x32_bf16 v[104:107], v[164:167], v[198:201], v[104:107]
	v_mfma_f32_16x16x32_bf16 v[92:95], v[156:159], v[206:209], v[92:95]
	v_mfma_f32_16x16x32_bf16 v[88:91], v[164:167], v[206:209], v[88:91]
	v_mfma_f32_16x16x32_bf16 v[76:79], v[156:159], v[214:217], v[76:79]
	v_mfma_f32_16x16x32_bf16 v[72:75], v[164:167], v[214:217], v[72:75]
	v_mfma_f32_16x16x32_bf16 v[124:127], v[160:163], v[192:195], v[124:127]
	v_mfma_f32_16x16x32_bf16 v[120:123], v[168:171], v[192:195], v[120:123]
	v_mfma_f32_16x16x32_bf16 v[108:111], v[160:163], v[202:205], v[108:111]
	v_mfma_f32_16x16x32_bf16 v[104:107], v[168:171], v[202:205], v[104:107]
	v_mfma_f32_16x16x32_bf16 v[92:95], v[160:163], v[210:213], v[92:95]
	v_mfma_f32_16x16x32_bf16 v[88:91], v[168:171], v[210:213], v[88:91]
	v_mfma_f32_16x16x32_bf16 v[76:79], v[160:163], v[218:221], v[76:79]
	v_mfma_f32_16x16x32_bf16 v[72:75], v[168:171], v[218:221], v[72:75]
	s_setprio 0
	s_setprio 1
	v_mfma_f32_16x16x32_bf16 v[116:119], v[172:175], v[188:191], v[116:119]
	v_mfma_f32_16x16x32_bf16 v[112:115], v[180:183], v[188:191], v[112:115]
	v_mfma_f32_16x16x32_bf16 v[100:103], v[172:175], v[198:201], v[100:103]
	v_mfma_f32_16x16x32_bf16 v[96:99], v[180:183], v[198:201], v[96:99]
	v_mfma_f32_16x16x32_bf16 v[84:87], v[172:175], v[206:209], v[84:87]
	v_mfma_f32_16x16x32_bf16 v[80:83], v[180:183], v[206:209], v[80:83]
	v_mfma_f32_16x16x32_bf16 v[68:71], v[172:175], v[214:217], v[68:71]
	v_mfma_f32_16x16x32_bf16 v[64:67], v[180:183], v[214:217], v[64:67]
	v_mfma_f32_16x16x32_bf16 v[116:119], v[176:179], v[192:195], v[116:119]
	v_mfma_f32_16x16x32_bf16 v[112:115], v[184:187], v[192:195], v[112:115]
	v_mfma_f32_16x16x32_bf16 v[100:103], v[176:179], v[202:205], v[100:103]
	v_mfma_f32_16x16x32_bf16 v[96:99], v[184:187], v[202:205], v[96:99]
	v_mfma_f32_16x16x32_bf16 v[84:87], v[176:179], v[210:213], v[84:87]
	v_mfma_f32_16x16x32_bf16 v[80:83], v[184:187], v[210:213], v[80:83]
	v_mfma_f32_16x16x32_bf16 v[68:71], v[176:179], v[218:221], v[68:71]
	v_mfma_f32_16x16x32_bf16 v[64:67], v[184:187], v[218:221], v[64:67]
	s_setprio 0
	s_barrier
	s_add_i32 s44, s64, s2
	v_lshl_add_u64 v[148:149], v[148:149], 0, s[16:17]
	s_mov_b32 m0, s44
	ds_read_b128 v[188:191], v153 offset:49152
	ds_read_b128 v[192:195], v153 offset:50176
	ds_read_b128 v[198:201], v153 offset:51200
	ds_read_b128 v[202:205], v153 offset:52224
	ds_read_b128 v[206:209], v153 offset:53248
	ds_read_b128 v[210:213], v153 offset:54272
	ds_read_b128 v[214:217], v153 offset:55296
	ds_read_b128 v[218:221], v153 offset:56320
	global_load_lds_dwordx4 v[148:149], off
	s_add_i32 m0, s44, 0x2000
	s_add_u32 s40, s40, 0x40080
	v_lshl_add_u64 v[148:149], v[222:223], 0, s[16:17]
	s_addc_u32 s41, s41, 0
	s_add_i32 s44, s65, s2
	global_load_lds_dwordx4 v[148:149], off
	v_lshl_add_u64 v[148:149], s[40:41], 0, v[132:133]
	s_mov_b32 m0, s44
	s_nop 0
	global_load_lds_dwordx4 v[148:149], off
	v_lshl_add_u64 v[148:149], s[40:41], 0, v[128:129]
	s_add_i32 m0, s44, 0x2000
	s_nop 0
	global_load_lds_dwordx4 v[148:149], off
	v_lshl_add_u64 v[148:149], v[224:225], 0, s[16:17]
	s_mov_b32 m0, s54
	s_nop 0
	global_load_lds_dwordx4 v[148:149], off
	v_lshl_add_u64 v[148:149], v[226:227], 0, s[16:17]
	s_mov_b32 m0, s55
	s_nop 0
	global_load_lds_dwordx4 v[148:149], off
	s_waitcnt vmcnt(8)
	s_waitcnt lgkmcnt(0)
	s_barrier
	s_setprio 1
	s_waitcnt lgkmcnt(0)
	v_mfma_f32_16x16x32_bf16 v[60:63], v[156:159], v[188:191], v[60:63]
	v_mfma_f32_16x16x32_bf16 v[56:59], v[164:167], v[188:191], v[56:59]
	v_mfma_f32_16x16x32_bf16 v[44:47], v[156:159], v[198:201], v[44:47]
	v_mfma_f32_16x16x32_bf16 v[40:43], v[164:167], v[198:201], v[40:43]
	v_mfma_f32_16x16x32_bf16 v[28:31], v[156:159], v[206:209], v[28:31]
	v_mfma_f32_16x16x32_bf16 v[24:27], v[164:167], v[206:209], v[24:27]
	v_mfma_f32_16x16x32_bf16 v[12:15], v[156:159], v[214:217], v[12:15]
	v_mfma_f32_16x16x32_bf16 v[8:11], v[164:167], v[214:217], v[8:11]
	v_mfma_f32_16x16x32_bf16 v[60:63], v[160:163], v[192:195], v[60:63]
	v_mfma_f32_16x16x32_bf16 v[56:59], v[168:171], v[192:195], v[56:59]
	v_mfma_f32_16x16x32_bf16 v[44:47], v[160:163], v[202:205], v[44:47]
	v_mfma_f32_16x16x32_bf16 v[40:43], v[168:171], v[202:205], v[40:43]
	v_mfma_f32_16x16x32_bf16 v[28:31], v[160:163], v[210:213], v[28:31]
	v_mfma_f32_16x16x32_bf16 v[24:27], v[168:171], v[210:213], v[24:27]
	v_mfma_f32_16x16x32_bf16 v[12:15], v[160:163], v[218:221], v[12:15]
	v_mfma_f32_16x16x32_bf16 v[8:11], v[168:171], v[218:221], v[8:11]
	s_setprio 0
	s_setprio 1
	v_mfma_f32_16x16x32_bf16 v[52:55], v[172:175], v[188:191], v[52:55]
	v_mfma_f32_16x16x32_bf16 v[48:51], v[180:183], v[188:191], v[48:51]
	v_mfma_f32_16x16x32_bf16 v[36:39], v[172:175], v[198:201], v[36:39]
	v_mfma_f32_16x16x32_bf16 v[32:35], v[180:183], v[198:201], v[32:35]
	v_mfma_f32_16x16x32_bf16 v[20:23], v[172:175], v[206:209], v[20:23]
	v_mfma_f32_16x16x32_bf16 v[16:19], v[180:183], v[206:209], v[16:19]
	v_mfma_f32_16x16x32_bf16 v[4:7], v[172:175], v[214:217], v[4:7]
	v_mfma_f32_16x16x32_bf16 v[0:3], v[180:183], v[214:217], v[0:3]
	v_mfma_f32_16x16x32_bf16 v[52:55], v[176:179], v[192:195], v[52:55]
	v_mfma_f32_16x16x32_bf16 v[48:51], v[184:187], v[192:195], v[48:51]
	v_mfma_f32_16x16x32_bf16 v[36:39], v[176:179], v[202:205], v[36:39]
	v_mfma_f32_16x16x32_bf16 v[32:35], v[184:187], v[202:205], v[32:35]
	v_mfma_f32_16x16x32_bf16 v[20:23], v[176:179], v[210:213], v[20:23]
	v_mfma_f32_16x16x32_bf16 v[16:19], v[184:187], v[210:213], v[16:19]
	v_mfma_f32_16x16x32_bf16 v[4:7], v[176:179], v[218:221], v[4:7]
	v_mfma_f32_16x16x32_bf16 v[0:3], v[184:187], v[218:221], v[0:3]
	s_setprio 0
	s_barrier
	s_add_i32 s63, s63, 2
	s_add_u32 s36, s36, 0x100
	s_addc_u32 s37, s37, 0
	s_add_u32 s61, s61, 0x100
	s_addc_u32 s62, s62, 0
